# v47 + final rmsnorm phase: next iteration's x rows prefetched one iteration ahead into a spare register set
# baseline (speedup 1.0000x reference)
.LBB0_898:
	s_or_b64 exec, exec, s[0:1]
	s_waitcnt lgkmcnt(0)
	v_mov_b32_e32 v0, v182
	s_barrier
	v_readlane_b32 s0, v252, 0
	v_ashrrev_i32_e32 v0, 5, v0
	v_and_b32_e32 v0, -2, v0
	v_lshl_add_u32 v16, s0, 4, v0
	s_movk_i32 s0, 0x4000
	v_cmp_gt_i32_e32 vcc, s0, v16
	s_and_saveexec_b64 s[0:1], vcc
	s_cbranch_execz .LBB0_901
	v_lshlrev_b32_e32 v0, 2, v182
	v_and_b32_e32 v18, 0xfc, v0
	v_mov_b32_e32 v1, 0
	v_lshlrev_b32_e32 v0, 2, v18
	v_lshl_add_u64 v[20:21], s[54:55], 0, v[0:1]
	s_mov_b64 s[0:1], 0x1000
	v_lshl_add_u64 v[22:23], v[20:21], 0, s[0:1]
	s_mov_b64 s[0:1], 0x1400
	v_lshl_add_u64 v[24:25], v[20:21], 0, s[0:1]
	s_mov_b64 s[0:1], 0x1800
	v_lshl_add_u64 v[26:27], v[20:21], 0, s[0:1]
	s_mov_b64 s[0:1], 0x1c00
	s_lshl_b32 s5, s96, 4
	v_lshl_add_u64 v[28:29], v[20:21], 0, s[0:1]
	s_mov_b64 s[2:3], 0
	s_movk_i32 s8, 0x2000
	s_movk_i32 s9, 0x1000
	s_movk_i32 s10, 0x3000
	s_mov_b32 s4, 0x3a000000
	s_mov_b32 s11, 0x800000
	s_movk_i32 s12, 0x3fff
	v_mov_b32_e32 v30, 0x358637bd
	global_load_dwordx4 v[140:143], v[20:21], off
	global_load_dwordx4 v[144:147], v[20:21], off offset:1024
	global_load_dwordx4 v[148:151], v[20:21], off offset:2048
	global_load_dwordx4 v[152:155], v[20:21], off offset:3072
	global_load_dwordx4 v[156:159], v[22:23], off
	global_load_dwordx4 v[160:163], v[24:25], off
	global_load_dwordx4 v[164:167], v[26:27], off
	global_load_dwordx4 v[168:171], v[28:29], off
	s_waitcnt vmcnt(0)
	v_min_i32_e32 v172, 0x3ffe, v16
	v_lshlrev_b32_e32 v172, 13, v172
	v_lshl_add_u32 v172, v18, 2, v172
	v_add_u32_e32 v173, 0x1000, v172
	v_add_u32_e32 v174, 0x2000, v172
	v_add_u32_e32 v175, 0x3000, v172
	global_load_dwordx4 v[184:187], v172, s[52:53]
	global_load_dwordx4 v[188:191], v172, s[52:53] offset:1024
	global_load_dwordx4 v[192:195], v172, s[52:53] offset:2048
	global_load_dwordx4 v[196:199], v172, s[52:53] offset:3072
	global_load_dwordx4 v[200:203], v174, s[52:53]
	global_load_dwordx4 v[204:207], v174, s[52:53] offset:1024
	global_load_dwordx4 v[208:211], v174, s[52:53] offset:2048
	global_load_dwordx4 v[212:215], v174, s[52:53] offset:3072
	global_load_dwordx4 v[216:219], v173, s[52:53]
	global_load_dwordx4 v[220:223], v173, s[52:53] offset:1024
	global_load_dwordx4 v[224:227], v173, s[52:53] offset:2048
	global_load_dwordx4 v[228:231], v173, s[52:53] offset:3072
	global_load_dwordx4 v[232:235], v175, s[52:53]
	global_load_dwordx4 v[236:239], v175, s[52:53] offset:1024
	global_load_dwordx4 v[240:243], v175, s[52:53] offset:2048
	global_load_dwordx4 v[244:247], v175, s[52:53] offset:3072
.LBB0_900:
	v_ashrrev_i32_e32 v17, 31, v16
	v_lshlrev_b64 v[0:1], 11, v[16:17]
	v_or_b32_e32 v0, v0, v18
	v_lshlrev_b64 v[32:33], 2, v[0:1]
	v_lshl_add_u64 v[2:3], v[0:1], 1, s[6:7]
	v_lshl_add_u64 v[0:1], s[52:53], 0, v[32:33]
	v_add_co_u32_e32 v4, vcc, 0x2000, v0
	s_mov_b64 s[0:1], vcc
	v_add_co_u32_e32 v6, vcc, 0x1000, v2
	global_load_dwordx2 v[58:59], v[2:3], off
	global_load_dwordx2 v[60:61], v[2:3], off offset:512
	global_load_dwordx2 v[68:69], v[2:3], off offset:1024
	v_addc_co_u32_e32 v7, vcc, 0, v3, vcc
	global_load_dwordx2 v[70:71], v[6:7], off
	global_load_dwordx2 v[72:73], v[6:7], off offset:512
	v_addc_co_u32_e64 v5, vcc, 0, v1, s[0:1]
	global_load_dwordx2 v[106:107], v[6:7], off offset:1024
	global_load_dwordx2 v[108:109], v[2:3], off offset:1536
	global_load_dwordx2 v[122:123], v[6:7], off offset:1536
	global_load_dwordx2 v[124:125], v[2:3], off offset:2048
	global_load_dwordx2 v[126:127], v[2:3], off offset:2560
	global_load_dwordx2 v[102:103], v[2:3], off offset:3072
	global_load_dwordx2 v[100:101], v[2:3], off offset:3584
	v_add_co_u32_e32 v62, vcc, s9, v0
	global_load_dwordx2 v[128:129], v[6:7], off offset:2048
	global_load_dwordx2 v[130:131], v[6:7], off offset:2560
	global_load_dwordx2 v[104:105], v[6:7], off offset:3072
	global_load_dwordx2 v[98:99], v[6:7], off offset:3584
	v_addc_co_u32_e32 v63, vcc, 0, v1, vcc
	v_add_co_u32_e32 v82, vcc, s10, v0
	v_add_u32_e32 v16, s5, v16
	s_nop 0
	v_addc_co_u32_e32 v83, vcc, 0, v1, vcc
	s_waitcnt vmcnt(0)
	v_mov_b64_e32 v[34:35], v[184:185]
	v_mov_b64_e32 v[36:37], v[186:187]
	v_mov_b64_e32 v[38:39], v[188:189]
	v_mov_b64_e32 v[40:41], v[190:191]
	v_mov_b64_e32 v[50:51], v[192:193]
	v_mov_b64_e32 v[52:53], v[194:195]
	v_mov_b64_e32 v[64:65], v[196:197]
	v_mov_b64_e32 v[66:67], v[198:199]
	v_mov_b64_e32 v[42:43], v[200:201]
	v_mov_b64_e32 v[44:45], v[202:203]
	v_mov_b64_e32 v[46:47], v[204:205]
	v_mov_b64_e32 v[48:49], v[206:207]
	v_mov_b64_e32 v[54:55], v[208:209]
	v_mov_b64_e32 v[56:57], v[210:211]
	v_mov_b64_e32 v[74:75], v[212:213]
	v_mov_b64_e32 v[76:77], v[214:215]
	v_mov_b64_e32 v[78:79], v[216:217]
	v_mov_b64_e32 v[80:81], v[218:219]
	v_mov_b64_e32 v[110:111], v[220:221]
	v_mov_b64_e32 v[112:113], v[222:223]
	v_mov_b64_e32 v[12:13], v[224:225]
	v_mov_b64_e32 v[14:15], v[226:227]
	v_mov_b64_e32 v[4:5], v[228:229]
	v_mov_b64_e32 v[6:7], v[230:231]
	v_mov_b64_e32 v[114:115], v[232:233]
	v_mov_b64_e32 v[116:117], v[234:235]
	v_mov_b64_e32 v[118:119], v[236:237]
	v_mov_b64_e32 v[120:121], v[238:239]
	v_mov_b64_e32 v[8:9], v[240:241]
	v_mov_b64_e32 v[10:11], v[242:243]
	v_mov_b64_e32 v[0:1], v[244:245]
	v_mov_b64_e32 v[2:3], v[246:247]
	v_min_i32_e32 v172, 0x3ffe, v16
	v_lshlrev_b32_e32 v172, 13, v172
	v_lshl_add_u32 v172, v18, 2, v172
	v_add_u32_e32 v173, 0x1000, v172
	v_add_u32_e32 v174, 0x2000, v172
	v_add_u32_e32 v175, 0x3000, v172
	global_load_dwordx4 v[184:187], v172, s[52:53]
	global_load_dwordx4 v[188:191], v172, s[52:53] offset:1024
	global_load_dwordx4 v[192:195], v172, s[52:53] offset:2048
	global_load_dwordx4 v[196:199], v172, s[52:53] offset:3072
	global_load_dwordx4 v[200:203], v174, s[52:53]
	global_load_dwordx4 v[204:207], v174, s[52:53] offset:1024
	global_load_dwordx4 v[208:211], v174, s[52:53] offset:2048
	global_load_dwordx4 v[212:215], v174, s[52:53] offset:3072
	global_load_dwordx4 v[216:219], v173, s[52:53]
	global_load_dwordx4 v[220:223], v173, s[52:53] offset:1024
	global_load_dwordx4 v[224:227], v173, s[52:53] offset:2048
	global_load_dwordx4 v[228:231], v173, s[52:53] offset:3072
	global_load_dwordx4 v[232:235], v175, s[52:53]
	global_load_dwordx4 v[236:239], v175, s[52:53] offset:1024
	global_load_dwordx4 v[240:243], v175, s[52:53] offset:2048
	global_load_dwordx4 v[244:247], v175, s[52:53] offset:3072
	v_lshlrev_b32_e32 v62, 16, v58
	v_and_b32_e32 v63, 0xffff0000, v58
	v_lshlrev_b32_e32 v58, 16, v59
	v_and_b32_e32 v59, 0xffff0000, v59
	v_lshlrev_b32_e32 v82, 16, v60
	v_and_b32_e32 v83, 0xffff0000, v60
	v_lshlrev_b32_e32 v84, 16, v61
	v_and_b32_e32 v85, 0xffff0000, v61
	v_pk_add_f32 v[60:61], v[34:35], v[62:63]
	v_pk_add_f32 v[62:63], v[36:37], v[58:59]
	v_pk_add_f32 v[34:35], v[38:39], v[82:83]
	v_pk_add_f32 v[36:37], v[40:41], v[84:85]
	v_lshlrev_b32_e32 v38, 16, v70
	v_and_b32_e32 v39, 0xffff0000, v70
	v_lshlrev_b32_e32 v40, 16, v71
	v_and_b32_e32 v41, 0xffff0000, v71
	v_lshlrev_b32_e32 v58, 16, v72
	v_and_b32_e32 v59, 0xffff0000, v72
	v_lshlrev_b32_e32 v132, 16, v68
	v_lshlrev_b32_e32 v82, 16, v73
	v_and_b32_e32 v83, 0xffff0000, v73
	v_pk_add_f32 v[70:71], v[42:43], v[38:39]
	v_pk_add_f32 v[72:73], v[44:45], v[40:41]
	v_pk_add_f32 v[40:41], v[46:47], v[58:59]
	v_and_b32_e32 v133, 0xffff0000, v68
	v_lshlrev_b32_e32 v42, 16, v69
	v_and_b32_e32 v43, 0xffff0000, v69
	v_lshlrev_b32_e32 v46, 16, v107
	v_and_b32_e32 v47, 0xffff0000, v107
	v_pk_add_f32 v[38:39], v[50:51], v[132:133]
	v_pk_add_f32 v[50:51], v[52:53], v[42:43]
	v_pk_add_f32 v[52:53], v[56:57], v[46:47]
	v_lshlrev_b32_e32 v46, 16, v108
	v_and_b32_e32 v47, 0xffff0000, v108
	v_pk_add_f32 v[46:47], v[64:65], v[46:47]
	v_pk_add_f32 v[44:45], v[48:49], v[82:83]
	v_lshlrev_b32_e32 v42, 16, v106
	v_and_b32_e32 v43, 0xffff0000, v106
	v_lshlrev_b32_e32 v48, 16, v109
	v_and_b32_e32 v49, 0xffff0000, v109
	v_mov_b32_e32 v64, v39
	v_mov_b32_e32 v65, v47
	v_pk_add_f32 v[42:43], v[54:55], v[42:43]
	v_pk_add_f32 v[54:55], v[66:67], v[48:49]
	v_mov_b32_e32 v58, v38
	v_mov_b32_e32 v59, v46
	v_pk_mul_f32 v[64:65], v[64:65], v[64:65]
	v_lshlrev_b32_e32 v48, 16, v122
	v_and_b32_e32 v49, 0xffff0000, v122
	v_pk_fma_f32 v[58:59], v[58:59], v[58:59], v[64:65]
	v_mov_b32_e32 v64, v50
	v_mov_b32_e32 v65, v54
	v_pk_add_f32 v[48:49], v[74:75], v[48:49]
	v_pk_fma_f32 v[58:59], v[64:65], v[64:65], v[58:59]
	v_mov_b32_e32 v64, v51
	v_mov_b32_e32 v65, v55
	v_lshlrev_b32_e32 v56, 16, v123
	v_and_b32_e32 v57, 0xffff0000, v123
	v_pk_fma_f32 v[108:109], v[64:65], v[64:65], v[58:59]
	v_mov_b32_e32 v64, v43
	v_mov_b32_e32 v65, v49
	v_pk_add_f32 v[56:57], v[76:77], v[56:57]
	v_mov_b32_e32 v58, v42
	v_mov_b32_e32 v59, v48
	v_pk_mul_f32 v[64:65], v[64:65], v[64:65]
	v_lshlrev_b32_e32 v68, 16, v127
	v_pk_fma_f32 v[58:59], v[58:59], v[58:59], v[64:65]
	v_mov_b32_e32 v64, v52
	v_mov_b32_e32 v65, v56
	v_pk_fma_f32 v[58:59], v[64:65], v[64:65], v[58:59]
	v_mov_b32_e32 v64, v53
	v_mov_b32_e32 v65, v57
	v_pk_fma_f32 v[106:107], v[64:65], v[64:65], v[58:59]
	v_lshlrev_b32_e32 v64, 16, v125
	v_and_b32_e32 v65, 0xffff0000, v125
	v_pk_add_f32 v[74:75], v[80:81], v[64:65]
	v_lshlrev_b32_e32 v64, 16, v128
	v_and_b32_e32 v65, 0xffff0000, v128
	v_lshlrev_b32_e32 v58, 16, v124
	v_and_b32_e32 v59, 0xffff0000, v124
	v_pk_add_f32 v[66:67], v[114:115], v[64:65]
	v_lshlrev_b32_e32 v64, 16, v129
	v_and_b32_e32 v65, 0xffff0000, v129
	v_pk_add_f32 v[58:59], v[78:79], v[58:59]
	v_pk_add_f32 v[78:79], v[116:117], v[64:65]
	v_lshlrev_b32_e32 v64, 16, v126
	v_and_b32_e32 v65, 0xffff0000, v126
	v_pk_add_f32 v[64:65], v[110:111], v[64:65]
	v_and_b32_e32 v69, 0xffff0000, v127
	v_pk_add_f32 v[76:77], v[112:113], v[68:69]
	v_mov_b32_e32 v112, v59
	v_mov_b32_e32 v113, v65
	v_lshlrev_b32_e32 v68, 16, v130
	v_and_b32_e32 v69, 0xffff0000, v130
	v_mov_b32_e32 v110, v58
	v_mov_b32_e32 v111, v64
	v_pk_mul_f32 v[112:113], v[112:113], v[112:113]
	v_pk_add_f32 v[68:69], v[118:119], v[68:69]
	v_pk_fma_f32 v[110:111], v[110:111], v[110:111], v[112:113]
	v_mov_b32_e32 v112, v74
	v_mov_b32_e32 v113, v76
	v_lshlrev_b32_e32 v80, 16, v131
	v_and_b32_e32 v81, 0xffff0000, v131
	v_pk_fma_f32 v[110:111], v[112:113], v[112:113], v[110:111]
	v_mov_b32_e32 v112, v75
	v_mov_b32_e32 v113, v77
	v_mov_b32_e32 v114, v67
	v_mov_b32_e32 v115, v69
	v_pk_add_f32 v[80:81], v[120:121], v[80:81]
	v_pk_fma_f32 v[110:111], v[112:113], v[112:113], v[110:111]
	v_mov_b32_e32 v112, v66
	v_mov_b32_e32 v113, v68
	v_pk_mul_f32 v[114:115], v[114:115], v[114:115]
	v_pk_mul_f32 v[92:93], v[60:61], v[60:61]
	v_pk_fma_f32 v[112:113], v[112:113], v[112:113], v[114:115]
	v_mov_b32_e32 v114, v78
	v_mov_b32_e32 v115, v80
	v_pk_fma_f32 v[112:113], v[114:115], v[114:115], v[112:113]
	v_mov_b32_e32 v114, v79
	v_mov_b32_e32 v115, v81
	v_pk_fma_f32 v[112:113], v[114:115], v[114:115], v[112:113]
	v_lshlrev_b32_e32 v114, 16, v102
	v_and_b32_e32 v115, 0xffff0000, v102
	v_lshlrev_b32_e32 v102, 16, v103
	v_and_b32_e32 v103, 0xffff0000, v103
	v_pk_add_f32 v[14:15], v[14:15], v[102:103]
	v_lshlrev_b32_e32 v102, 16, v104
	v_and_b32_e32 v103, 0xffff0000, v104
	v_pk_add_f32 v[8:9], v[8:9], v[102:103]
	v_lshlrev_b32_e32 v102, 16, v105
	v_and_b32_e32 v103, 0xffff0000, v105
	v_pk_add_f32 v[10:11], v[10:11], v[102:103]
	v_lshlrev_b32_e32 v102, 16, v100
	v_and_b32_e32 v103, 0xffff0000, v100
	v_lshlrev_b32_e32 v100, 16, v101
	v_and_b32_e32 v101, 0xffff0000, v101
	v_pk_add_f32 v[12:13], v[12:13], v[114:115]
	v_pk_add_f32 v[4:5], v[4:5], v[102:103]
	v_pk_add_f32 v[6:7], v[6:7], v[100:101]
	v_lshlrev_b32_e32 v100, 16, v98
	v_and_b32_e32 v101, 0xffff0000, v98
	v_pk_add_f32 v[0:1], v[0:1], v[100:101]
	v_lshlrev_b32_e32 v98, 16, v99
	v_and_b32_e32 v99, 0xffff0000, v99
	v_mov_b32_e32 v100, v13
	v_mov_b32_e32 v101, v5
	v_pk_add_f32 v[2:3], v[2:3], v[98:99]
	v_mov_b32_e32 v98, v12
	v_mov_b32_e32 v99, v4
	v_pk_mul_f32 v[100:101], v[100:101], v[100:101]
	v_pk_mul_f32 v[96:97], v[34:35], v[34:35]
	v_pk_fma_f32 v[102:103], v[98:99], v[98:99], v[100:101]
	s_nop 1
	v_mov_b64_e32 v[98:99], v[140:141]
	v_mov_b64_e32 v[100:101], v[142:143]
	v_pk_mul_f32 v[90:91], v[62:63], v[62:63]
	v_pk_mul_f32 v[94:95], v[36:37], v[36:37]
	v_add_f32_e32 v17, v96, v97
	v_add_f32_e32 v19, v92, v93
	v_add_f32_e32 v17, v94, v17
	v_add_f32_e32 v19, v90, v19
	v_add_f32_e32 v17, v95, v17
	v_add_f32_e32 v19, v91, v19
	v_pk_mul_f32 v[84:85], v[70:71], v[70:71]
	v_pk_mul_f32 v[88:89], v[40:41], v[40:41]
	v_add_f32_e32 v17, v19, v17
	v_pk_mul_f32 v[82:83], v[72:73], v[72:73]
	v_pk_mul_f32 v[86:87], v[44:45], v[44:45]
	v_add_f32_e32 v17, v17, v108
	v_add_f32_e32 v19, v88, v89
	v_add_f32_e32 v31, v84, v85
	v_mov_b32_e32 v104, v14
	v_mov_b32_e32 v105, v6
	v_add_f32_e32 v17, v17, v109
	v_add_f32_e32 v19, v86, v19
	v_add_f32_e32 v31, v82, v31
	v_pk_fma_f32 v[102:103], v[104:105], v[104:105], v[102:103]
	v_mov_b32_e32 v104, v15
	v_mov_b32_e32 v105, v7
	v_add_f32_e32 v17, v17, v110
	v_add_f32_e32 v19, v87, v19
	v_add_f32_e32 v31, v83, v31
	v_pk_fma_f32 v[102:103], v[104:105], v[104:105], v[102:103]
	v_add_f32_e32 v17, v17, v111
	v_mov_b32_e32 v92, v9
	v_mov_b32_e32 v93, v1
	v_add_f32_e32 v19, v31, v19
	v_add_f32_e32 v17, v17, v102
	v_mov_b32_e32 v90, v8
	v_mov_b32_e32 v91, v0
	v_pk_mul_f32 v[92:93], v[92:93], v[92:93]
	v_add_f32_e32 v19, v19, v106
	v_add_f32_e32 v17, v17, v103
	v_pk_fma_f32 v[90:91], v[90:91], v[90:91], v[92:93]
	v_mov_b32_e32 v92, v10
	v_mov_b32_e32 v93, v2
	v_add_f32_e32 v19, v19, v107
	v_pk_fma_f32 v[90:91], v[92:93], v[92:93], v[90:91]
	v_mov_b32_e32 v92, v11
	v_mov_b32_e32 v93, v3
	v_add_f32_e32 v19, v19, v112
	v_add_f32_dpp v17, v17, v17 quad_perm:[1,0,3,2] row_mask:0xf bank_mask:0xf bound_ctrl:1
	v_pk_fma_f32 v[90:91], v[92:93], v[92:93], v[90:91]
	v_add_f32_e32 v19, v19, v113
	v_add_f32_dpp v17, v17, v17 quad_perm:[2,3,0,1] row_mask:0xf bank_mask:0xf bound_ctrl:1
	v_add_f32_e32 v19, v19, v90
	v_add_f32_e32 v19, v19, v91
	v_add_f32_dpp v17, v17, v17 row_half_mirror row_mask:0xf bank_mask:0xf bound_ctrl:1
	v_lshl_add_u64 v[86:87], s[56:57], 0, v[32:33]
	s_nop 0
	v_add_f32_dpp v17, v17, v17 row_mirror row_mask:0xf bank_mask:0xf bound_ctrl:1
	s_nop 0
	v_readlane_b32 s1, v17, 0
	v_readlane_b32 s13, v17, 16
	v_readlane_b32 s15, v17, 32
	v_readlane_b32 s17, v17, 48
	v_add_f32_dpp v17, v19, v19 quad_perm:[1,0,3,2] row_mask:0xf bank_mask:0xf bound_ctrl:1
	v_mov_b32_e32 v83, s13
	s_nop 0
	v_add_f32_dpp v17, v17, v17 quad_perm:[2,3,0,1] row_mask:0xf bank_mask:0xf bound_ctrl:1
	s_nop 1
	v_add_f32_dpp v17, v17, v17 row_half_mirror row_mask:0xf bank_mask:0xf bound_ctrl:1
	s_nop 1
	v_add_f32_dpp v17, v17, v17 row_mirror row_mask:0xf bank_mask:0xf bound_ctrl:1
	s_nop 0
	v_readlane_b32 s18, v17, 16
	v_readlane_b32 s0, v17, 0
	v_readlane_b32 s14, v17, 32
	v_mov_b32_e32 v82, s18
	v_pk_add_f32 v[82:83], s[0:1], v[82:83]
	v_readlane_b32 s16, v17, 48
	v_pk_add_f32 v[82:83], v[82:83], s[14:15]
	s_nop 0
	v_pk_add_f32 v[82:83], v[82:83], s[16:17]
	s_nop 0
	v_pk_fma_f32 v[82:83], v[82:83], s[4:5], v[30:31] op_sel_hi:[1,0,0]
	s_nop 0
	v_mul_f32_e32 v17, 0x4b800000, v83
	v_cmp_gt_f32_e32 vcc, s11, v83
	v_mul_f32_e32 v19, 0x4b800000, v82
	v_cmp_gt_f32_e64 s[0:1], s11, v82
	v_cndmask_b32_e32 v17, v83, v17, vcc
	v_rsq_f32_e32 v17, v17
	v_cndmask_b32_e64 v19, v82, v19, s[0:1]
	v_rsq_f32_e32 v19, v19
	v_mul_f32_e32 v31, 0x45800000, v17
	v_cndmask_b32_e32 v82, v17, v31, vcc
	v_mul_f32_e32 v17, 0x45800000, v19
	v_pk_mul_f32 v[60:61], v[60:61], v[82:83] op_sel_hi:[1,0]
	v_pk_mul_f32 v[62:63], v[62:63], v[82:83] op_sel_hi:[1,0]
	v_cndmask_b32_e64 v84, v19, v17, s[0:1]
	v_pk_mul_f32 v[62:63], v[100:101], v[62:63]
	v_pk_mul_f32 v[60:61], v[98:99], v[60:61]
	global_store_dwordx4 v[86:87], v[60:63], off
	v_pk_mul_f32 v[32:33], v[70:71], v[84:85] op_sel_hi:[1,0]
	v_add_co_u32_e32 v70, vcc, s10, v86
	v_pk_mul_f32 v[60:61], v[72:73], v[84:85] op_sel_hi:[1,0]
	s_nop 0
	v_addc_co_u32_e32 v71, vcc, 0, v87, vcc
	v_pk_mul_f32 v[62:63], v[100:101], v[60:61]
	v_pk_mul_f32 v[60:61], v[98:99], v[32:33]
	global_store_dwordx4 v[70:71], v[60:63], off offset:-4096
	s_nop 1
	v_mov_b64_e32 v[60:61], v[144:145]
	v_mov_b64_e32 v[62:63], v[146:147]
	v_pk_mul_f32 v[36:37], v[36:37], v[82:83] op_sel_hi:[1,0]
	v_pk_mul_f32 v[32:33], v[34:35], v[82:83] op_sel_hi:[1,0]
	v_add_co_u32_e32 v72, vcc, s8, v86
	v_pk_mul_f32 v[14:15], v[14:15], v[82:83] op_sel_hi:[1,0]
	s_nop 0
	v_addc_co_u32_e32 v73, vcc, 0, v87, vcc
	v_pk_mul_f32 v[12:13], v[12:13], v[82:83] op_sel_hi:[1,0]
	v_pk_mul_f32 v[6:7], v[6:7], v[82:83] op_sel_hi:[1,0]
	v_pk_mul_f32 v[4:5], v[4:5], v[82:83] op_sel_hi:[1,0]
	v_pk_mul_f32 v[32:33], v[32:33], v[60:61]
	v_pk_mul_f32 v[34:35], v[36:37], v[62:63]
	global_store_dwordx4 v[86:87], v[32:35], off offset:1024
	v_pk_mul_f32 v[36:37], v[38:39], v[82:83] op_sel_hi:[1,0]
	s_nop 0
	v_pk_mul_f32 v[34:35], v[44:45], v[84:85] op_sel_hi:[1,0]
	v_pk_mul_f32 v[32:33], v[40:41], v[84:85] op_sel_hi:[1,0]
	v_pk_mul_f32 v[34:35], v[62:63], v[34:35]
	v_pk_mul_f32 v[32:33], v[60:61], v[32:33]
	global_store_dwordx4 v[72:73], v[32:35], off offset:1024
	s_nop 1
	v_mov_b64_e32 v[32:33], v[148:149]
	v_mov_b64_e32 v[34:35], v[150:151]
	v_pk_mul_f32 v[40:41], v[50:51], v[82:83] op_sel_hi:[1,0]
	v_pk_mul_f32 v[44:45], v[66:67], v[84:85] op_sel_hi:[1,0]
	v_pk_mul_f32 v[36:37], v[36:37], v[32:33]
	v_pk_mul_f32 v[38:39], v[40:41], v[34:35]
	global_store_dwordx4 v[86:87], v[36:39], off offset:2048
	v_pk_mul_f32 v[40:41], v[56:57], v[84:85] op_sel_hi:[1,0]
	s_nop 0
	v_pk_mul_f32 v[36:37], v[52:53], v[84:85] op_sel_hi:[1,0]
	v_pk_mul_f32 v[38:39], v[42:43], v[84:85] op_sel_hi:[1,0]
	v_pk_mul_f32 v[34:35], v[34:35], v[36:37]
	v_pk_mul_f32 v[32:33], v[32:33], v[38:39]
	global_store_dwordx4 v[72:73], v[32:35], off offset:2048
	s_nop 1
	v_mov_b64_e32 v[32:33], v[152:153]
	v_mov_b64_e32 v[34:35], v[154:155]
	v_pk_mul_f32 v[38:39], v[54:55], v[82:83] op_sel_hi:[1,0]
	v_pk_mul_f32 v[36:37], v[46:47], v[82:83] op_sel_hi:[1,0]
	v_pk_mul_f32 v[42:43], v[48:49], v[84:85] op_sel_hi:[1,0]
	v_pk_mul_f32 v[36:37], v[36:37], v[32:33]
	v_pk_mul_f32 v[38:39], v[38:39], v[34:35]
	v_pk_mul_f32 v[32:33], v[32:33], v[42:43]
	v_pk_mul_f32 v[34:35], v[34:35], v[40:41]
	global_store_dwordx4 v[86:87], v[36:39], off offset:3072
	global_store_dwordx4 v[72:73], v[32:35], off offset:3072
	s_nop 1
	v_mov_b64_e32 v[32:33], v[156:157]
	v_mov_b64_e32 v[34:35], v[158:159]
	v_add_co_u32_e32 v40, vcc, s9, v86
	v_pk_mul_f32 v[38:39], v[74:75], v[82:83] op_sel_hi:[1,0]
	v_pk_mul_f32 v[36:37], v[58:59], v[82:83] op_sel_hi:[1,0]
	v_addc_co_u32_e32 v41, vcc, 0, v87, vcc
	v_pk_mul_f32 v[42:43], v[78:79], v[84:85] op_sel_hi:[1,0]
	v_cmp_lt_i32_e32 vcc, s12, v16
	s_or_b64 s[2:3], vcc, s[2:3]
	v_pk_mul_f32 v[36:37], v[36:37], v[32:33]
	v_pk_mul_f32 v[38:39], v[38:39], v[34:35]
	v_pk_mul_f32 v[32:33], v[44:45], v[32:33]
	v_pk_mul_f32 v[34:35], v[42:43], v[34:35]
	global_store_dwordx4 v[40:41], v[36:39], off
	global_store_dwordx4 v[70:71], v[32:35], off
	s_nop 1
	v_mov_b64_e32 v[32:33], v[160:161]
	v_mov_b64_e32 v[34:35], v[162:163]
	v_pk_mul_f32 v[38:39], v[76:77], v[82:83] op_sel_hi:[1,0]
	v_pk_mul_f32 v[36:37], v[64:65], v[82:83] op_sel_hi:[1,0]
	v_pk_mul_f32 v[42:43], v[80:81], v[84:85] op_sel_hi:[1,0]
	v_pk_mul_f32 v[44:45], v[68:69], v[84:85] op_sel_hi:[1,0]
	v_pk_mul_f32 v[36:37], v[36:37], v[32:33]
	v_pk_mul_f32 v[38:39], v[38:39], v[34:35]
	v_pk_mul_f32 v[32:33], v[44:45], v[32:33]
	v_pk_mul_f32 v[34:35], v[42:43], v[34:35]
	global_store_dwordx4 v[40:41], v[36:39], off offset:1024
	global_store_dwordx4 v[70:71], v[32:35], off offset:1024
	s_nop 1
	v_mov_b64_e32 v[32:33], v[164:165]
	v_mov_b64_e32 v[34:35], v[166:167]
	v_pk_mul_f32 v[36:37], v[10:11], v[84:85] op_sel_hi:[1,0]
	v_pk_mul_f32 v[38:39], v[8:9], v[84:85] op_sel_hi:[1,0]
	v_pk_mul_f32 v[8:9], v[12:13], v[32:33]
	v_pk_mul_f32 v[10:11], v[14:15], v[34:35]
	v_pk_mul_f32 v[12:13], v[38:39], v[32:33]
	v_pk_mul_f32 v[14:15], v[36:37], v[34:35]
	global_store_dwordx4 v[40:41], v[8:11], off offset:2048
	global_store_dwordx4 v[70:71], v[12:15], off offset:2048
	s_nop 1
	v_mov_b64_e32 v[8:9], v[168:169]
	v_mov_b64_e32 v[10:11], v[170:171]
	s_nop 0
	v_pk_mul_f32 v[12:13], v[2:3], v[84:85] op_sel_hi:[1,0]
	v_pk_mul_f32 v[14:15], v[0:1], v[84:85] op_sel_hi:[1,0]
	v_pk_mul_f32 v[0:1], v[4:5], v[8:9]
	v_pk_mul_f32 v[2:3], v[6:7], v[10:11]
	v_pk_mul_f32 v[4:5], v[14:15], v[8:9]
	v_pk_mul_f32 v[6:7], v[12:13], v[10:11]
	global_store_dwordx4 v[40:41], v[0:3], off offset:3072
	global_store_dwordx4 v[70:71], v[4:7], off offset:3072
	s_andn2_b64 exec, exec, s[2:3]
	s_cbranch_execnz .LBB0_900
